# dn_scan chain waves run at s_setprio 3 (chains now pinned one per CU), on top of v70
# speedup vs baseline: 1.0107x; 1.0036x over previous
; __device__ __forceinline__ int opaque_tid() { int t = threadIdx.x; asm volatile("" : "+v"(t)); return t; }
; __device__ void dn_scan(const P& p, int item, char* smem) {
;   const int tid = opaque_tid(), lane = tid & 63, w = tid >> 6, lr = lane & 15, quad = lane >> 4;
;   int dir, h, chunk0, nch;
;   if (item < 8) { h = item & 3; dir = (item >> 2) & 1; chunk0 = 0; nch = 256; }
;   else { int j = item - 8; h = j & 3; dir = (j >> 2) & 1; chunk0 = 256 + (j >> 3) * 32; nch = 32; }
;   constexpr int RS = 72;
;   constexpr int BUF = 3 * 64 * RS * 2 + 512;
;   bf16_t* UW = (bf16_t*)(p.ws + OFF_UW) + (size_t)dir * T * 512;
;   const bf16_t* KT = (const bf16_t*)(p.ws + OFF_KT);
;   const float* AB = (const float*)(p.ws + OFF_AB);
;   bf16_t* HST = (bf16_t*)(p.ws + OFF_HST);
;   f32x4 S[4];
; #pragma unroll
;   for (int dt = 0; dt < 4; ++dt) S[dt] = (f32x4){0.f, 0.f, 0.f, 0.f};
;     ...
;   RING(0) RING(1) RING(2) RING(3)
;     ...
;   const int lrow = tid >> 3, lch = tid & 7;
;     ...
;   SCAN_LOAD(0, 0) SCAN_LOAD(1, 1) SCAN_LOAD(2, 2) SCAN_LOAD(3, 3)
;   SCAN_STORE(0, 0)
;   SCAN_LOAD(0, 4)
;   __syncthreads();
.LBB0_529:
	s_andn2_b64 vcc, exec, s[0:1]
	s_cbranch_vccnz .LBB0_542
	s_setprio 3
	v_readlane_b32 s0, v254, 31
	s_mov_b32 s20, s0
	s_lshl_b32 s0, s0, 2
	s_and_b32 s0, s0, 0x7fffffe0
	s_addk_i32 s0, 0xe0
	s_bfe_u32 s18, s20, 0x10002
	s_cmp_lt_i32 s20, 8
	s_cselect_b32 s14, 0, s0
	s_cselect_b32 s15, 0x100, 32
	s_add_i32 s16, s14, s15
	s_add_i32 s2, s16, -3
	s_add_i32 s3, s16, -4
	s_or_b32 s4, s14, 3
	v_readlane_b32 s1, v254, 32
	s_cmp_eq_u32 s18, 0
	s_cselect_b64 s[0:1], -1, 0
	s_and_b64 s[0:1], s[0:1], exec
	s_cselect_b32 s8, s4, s3
	s_or_b32 s3, s14, 2
	s_cmp_eq_u32 s18, 0
	s_cselect_b64 s[0:1], -1, 0
	s_and_b64 s[0:1], s[0:1], exec
	s_cselect_b32 s10, s3, s2
	s_add_i32 s2, s16, -2
	s_or_b32 s3, s14, 1
	s_cmp_eq_u32 s18, 0
	s_cselect_b64 s[0:1], -1, 0
	s_and_b64 s[0:1], s[0:1], exec
	s_cselect_b32 s6, s3, s2
	s_add_i32 s4, s16, -1
	s_cmp_eq_u32 s18, 0
	s_cselect_b64 s[2:3], -1, 0
	s_mul_i32 s5, s18, 0x3000000
	s_and_b64 s[0:1], s[2:3], exec
	v_mov_b32_e32 v98, v220
	s_cselect_b32 s12, s14, s4
	s_add_u32 s4, s50, s5
	s_addc_u32 s5, s51, 0
	v_ashrrev_i32_e32 v128, 3, v98
	s_ashr_i32 s13, s12, 31
	s_lshl_b64 s[0:1], s[12:13], 6
	v_ashrrev_i32_e32 v129, 31, v128
	s_and_b32 s17, s20, 3
	v_lshl_add_u64 v[0:1], s[0:1], 0, v[128:129]
	s_lshl_b32 s7, s12, 2
	v_lshlrev_b64 v[0:1], 10, v[0:1]
	v_lshlrev_b32_e32 v2, 3, v98
	s_or_b32 s12, s7, s17
	v_lshl_add_u64 v[0:1], s[4:5], 0, v[0:1]
	s_lshl_b32 s82, s17, 7
	v_and_b32_e32 v99, 56, v2
	s_ashr_i32 s13, s12, 31
	v_lshl_add_u64 v[0:1], v[0:1], 0, s[82:83]
	v_lshlrev_b32_e32 v176, 1, v99
	s_lshl_b64 s[12:13], s[12:13], 13
	v_lshl_add_u64 v[0:1], v[0:1], 0, v[176:177]
	s_mov_b32 s47, 0x8000
	s_add_u32 s12, s22, s12
	v_add_co_u32_e32 v2, vcc, s47, v0
	v_lshlrev_b64 v[96:97], 7, v[128:129]
	s_addc_u32 s13, s23, s13
	s_ashr_i32 s7, s6, 31
	v_addc_co_u32_e32 v3, vcc, 0, v1, vcc
	global_load_dwordx4 v[72:75], v[0:1], off offset:512
	global_load_dwordx4 v[76:79], v[0:1], off
	global_load_dwordx4 v[80:83], v[2:3], off offset:512
	global_load_dwordx4 v[84:87], v[2:3], off
	v_lshl_add_u64 v[0:1], s[12:13], 0, v[96:97]
	s_lshl_b64 s[12:13], s[6:7], 6
	s_lshl_b32 s6, s6, 2
	v_lshl_add_u64 v[0:1], v[0:1], 0, v[176:177]
	s_movk_i32 s61, 0x1000
	s_or_b32 s6, s6, s17
	v_add_co_u32_e32 v2, vcc, s61, v0
	s_ashr_i32 s7, s6, 31
	s_nop 0
	v_addc_co_u32_e32 v3, vcc, 0, v1, vcc
	global_load_dwordx4 v[88:91], v[0:1], off
	global_load_dwordx4 v[92:95], v[2:3], off
	s_lshl_b32 s19, s18, 2
	v_lshl_add_u64 v[0:1], s[12:13], 0, v[128:129]
	s_lshl_b64 s[6:7], s[6:7], 13
	v_lshlrev_b64 v[0:1], 10, v[0:1]
	s_add_u32 s6, s22, s6
	v_lshl_add_u64 v[0:1], s[4:5], 0, v[0:1]
	s_addc_u32 s7, s23, s7
	s_ashr_i32 s11, s10, 31
	v_lshl_add_u64 v[0:1], v[0:1], 0, s[82:83]
	s_lshl_b64 s[20:21], s[10:11], 6
	s_lshl_b32 s9, s10, 2
	s_waitcnt vmcnt(55)
	v_lshl_add_u64 v[4:5], v[0:1], 0, v[176:177]
	s_waitcnt vmcnt(9)
	v_lshl_add_u64 v[26:27], s[20:21], 0, v[128:129]
	s_or_b32 s10, s9, s17
	v_and_b32_e32 v154, 63, v98
	v_add_co_u32_e32 v8, vcc, s47, v4
	v_lshl_add_u64 v[16:17], s[6:7], 0, v[96:97]
	v_lshlrev_b64 v[26:27], 10, v[26:27]
	s_ashr_i32 s11, s10, 31
	v_addc_co_u32_e32 v9, vcc, 0, v5, vcc
	v_lshl_add_u64 v[16:17], v[16:17], 0, v[176:177]
	v_or_b32_e32 v24, s12, v154
	v_mov_b32_e32 v25, s13
	s_lshl_b32 s12, s18, 4
	s_lshl_b32 s6, s17, 2
	v_lshl_add_u64 v[26:27], s[4:5], 0, v[26:27]
	s_lshl_b64 s[10:11], s[10:11], 13
	v_add_co_u32_e32 v20, vcc, s61, v16
	v_lshlrev_b64 v[24:25], 6, v[24:25]
	v_lshl_add_u64 v[26:27], v[26:27], 0, s[82:83]
	s_add_u32 s10, s22, s10
	v_addc_co_u32_e32 v21, vcc, 0, v17, vcc
	v_lshl_add_u64 v[24:25], s[86:87], 0, v[24:25]
	s_mov_b32 s13, s83
	v_lshl_add_u64 v[26:27], v[26:27], 0, v[176:177]
	s_addc_u32 s11, s23, s11
	s_waitcnt vmcnt(6)
	v_or_b32_e32 v46, s20, v154
	v_mov_b32_e32 v47, s21
	v_lshl_add_u64 v[24:25], v[24:25], 0, s[12:13]
	s_mov_b32 s7, s83
	v_add_co_u32_e32 v36, vcc, s47, v26
	v_lshl_add_u64 v[38:39], s[10:11], 0, v[96:97]
	v_lshlrev_b64 v[46:47], 6, v[46:47]
	v_lshl_add_u64 v[24:25], v[24:25], 0, s[6:7]
	v_addc_co_u32_e32 v37, vcc, 0, v27, vcc
	v_lshl_add_u64 v[44:45], v[38:39], 0, v[176:177]
	v_lshl_add_u64 v[46:47], s[86:87], 0, v[46:47]
	global_load_dwordx4 v[0:3], v[4:5], off offset:512
	s_nop 0
	global_load_dwordx4 v[4:7], v[4:5], off
	s_nop 0
	global_load_dwordx4 v[12:15], v[8:9], off offset:512
	s_nop 0
	global_load_dwordx4 v[8:11], v[8:9], off
	s_nop 0
	global_load_dwordx4 v[16:19], v[16:17], off
	s_nop 0
	global_load_dwordx4 v[20:23], v[20:21], off
	s_nop 0
	global_load_dword v155, v[24:25], off
	global_load_dwordx4 v[28:31], v[26:27], off
	s_nop 0
	global_load_dwordx4 v[24:27], v[26:27], off offset:512
	s_nop 0
	global_load_dwordx4 v[32:35], v[36:37], off
	s_nop 0
	global_load_dwordx4 v[36:39], v[36:37], off offset:512
	s_nop 0
	global_load_dwordx4 v[40:43], v[44:45], off
	v_add_co_u32_e32 v44, vcc, s61, v44
	v_lshl_add_u64 v[46:47], v[46:47], 0, s[12:13]
	s_ashr_i32 s9, s8, 31
	v_addc_co_u32_e32 v45, vcc, 0, v45, vcc
	v_lshl_add_u64 v[48:49], v[46:47], 0, s[6:7]
	s_lshl_b64 s[10:11], s[8:9], 6
	s_lshl_b32 s8, s8, 2
	global_load_dwordx4 v[44:47], v[44:45], off
	s_nop 0
	global_load_dword v156, v[48:49], off
	v_lshl_add_u64 v[48:49], s[10:11], 0, v[128:129]
	s_or_b32 s8, s8, s17
	v_lshlrev_b64 v[48:49], 10, v[48:49]
	s_ashr_i32 s9, s8, 31
	v_lshl_add_u64 v[48:49], s[4:5], 0, v[48:49]
	s_lshl_b64 s[8:9], s[8:9], 13
	v_lshl_add_u64 v[48:49], v[48:49], 0, s[82:83]
	s_add_u32 s8, s22, s8
	v_lshl_add_u64 v[52:53], v[48:49], 0, v[176:177]
	s_addc_u32 s9, s23, s9
	v_or_b32_e32 v100, s10, v154
	v_mov_b32_e32 v101, s11
	v_add_co_u32_e32 v56, vcc, s47, v52
	v_lshl_add_u64 v[64:65], s[8:9], 0, v[96:97]
	v_lshlrev_b64 v[100:101], 6, v[100:101]
	v_addc_co_u32_e32 v57, vcc, 0, v53, vcc
	v_lshl_add_u64 v[64:65], v[64:65], 0, v[176:177]
	v_lshl_add_u64 v[100:101], s[86:87], 0, v[100:101]
	global_load_dwordx4 v[48:51], v[52:53], off offset:512
	s_nop 0
	global_load_dwordx4 v[52:55], v[52:53], off
	s_nop 0
	global_load_dwordx4 v[60:63], v[56:57], off offset:512
	s_nop 0
	global_load_dwordx4 v[56:59], v[56:57], off
	v_add_co_u32_e32 v68, vcc, s61, v64
	v_lshl_add_u64 v[100:101], v[100:101], 0, s[12:13]
	s_nop 0
	v_addc_co_u32_e32 v69, vcc, 0, v65, vcc
	v_lshl_add_u64 v[100:101], v[100:101], 0, s[6:7]
	global_load_dwordx4 v[64:67], v[64:65], off
	s_nop 0
	global_load_dwordx4 v[68:71], v[68:69], off
	s_movk_i32 s8, 0x48
	global_load_dword v159, v[100:101], off
	v_mul_lo_u32 v100, v128, s8
	s_mov_b32 s41, 0x8000
	v_add_lshl_u32 v157, v100, v99, 1
	v_cmp_gt_i32_e32 vcc, 64, v98
	v_lshlrev_b32_e32 v158, 2, v98
	s_waitcnt vmcnt(26)
	ds_write_b128 v157, v[72:75]
	s_waitcnt vmcnt(24)
	ds_write_b128 v157, v[80:83] offset:4608
	s_waitcnt vmcnt(22)
	ds_write_b128 v157, v[88:91] offset:9216
	s_waitcnt vmcnt(21)
	ds_write_b128 v157, v[92:95] offset:13824
	ds_write_b128 v157, v[76:79] offset:18432
	ds_write_b128 v157, v[84:87] offset:23040
	s_and_saveexec_b64 s[8:9], vcc
	s_cbranch_execz .LBB0_532
	v_mov_b32_e32 v73, s1
	v_or_b32_e32 v72, s0, v154
	v_lshlrev_b64 v[72:73], 6, v[72:73]
	v_lshl_add_u64 v[72:73], s[86:87], 0, v[72:73]
	s_lshl_b32 s82, s19, 2
	v_lshl_add_u64 v[72:73], v[72:73], 0, s[82:83]
	v_lshl_add_u64 v[72:73], v[72:73], 0, s[6:7]
	global_load_dword v72, v[72:73], off
	s_waitcnt vmcnt(0)
	ds_write_b32 v158, v72 offset:27648

; #define SCAN_STEP(slotn, step) { \
;     SCAN_STORE(slotn, ((step) + 1) & 1) \
;     SCAN_LOAD(slotn, (step) + 5) \
;     scan_compute(step); \
;     lds_barrier(); }
; __device__ void dn_scan(const P& p, int item, char* smem) {
;     ...
; #pragma unroll 1
;   for (int s4 = 0; s4 < nch; s4 += 4) {
;     SCAN_STEP(1, s4)
;     SCAN_STEP(2, s4 + 1)
;     SCAN_STEP(3, s4 + 2)
;     SCAN_STEP(0, s4 + 3)
;   }
.LBB0_542:
	s_setprio 0
	s_mov_b64 s[0:1], 0
